# attention loops: one static s_setprio 1 for waves 4-7 (per-cluster toggles in the attention loops removed), reset at phase end
# baseline (speedup 1.0000x reference)
.LBB0_1018:
	v_readfirstlane_b32 s86, v166
	s_cmpk_lt_u32 s86, 0x100
	s_cbranch_scc1 .Lsp_n
	s_setprio 1

.LBB0_1269:
	v_readfirstlane_b32 s8, v166
	s_cmpk_lt_u32 s8, 0x100
	s_cbranch_scc1 .Lsp_d
	s_setprio 1

.LBB0_1914:
	s_setprio 0
	v_readlane_b32 s2, v254, 38
	v_readlane_b32 s0, v253, 2
	s_add_i32 s16, s2, 1
	s_cmpk_lg_i32 s89, 0x100
	s_cbranch_scc1 .Let_done
	s_cmp_eq_u32 s2, 7
	s_cbranch_scc0 .Let_not7
	v_readlane_b32 s3, v255, 22
	s_cmpk_lt_i32 s3, 0x80
	s_cbranch_scc1 .Let_done
	s_cmpk_lt_i32 s3, 0xa0
	s_cbranch_scc0 .Let_done
	s_mov_b32 s3, 1
	s_nop 0
	v_writelane_b32 v255, s3, 62
	s_mov_b32 s16, 8
	s_mov_b64 s[0:1], 0
	s_branch .LBB0_1969
